# v43 + FoX in-loop: forget-gate LDS reads issued ahead of the V-fragment reads, subs wait only for them (lgkmcnt 15), V reads drain under softmax
# baseline (speedup 1.0000x reference)
; #define LAS __attribute__((address_space(3)))
; template <int TY> __device__ __forceinline__ void attn_unit(LAS unsigned char* lds, const AttnArgs& a, int b, int h, int qt, int wave_s) {
;     ...
;         { const int Jn = J + 2 <= J1 ? J + 2 : J1; if (hf == 0) ATT_LOAD(A, Jn); else ATT_LOAD(B, Jn); }
;         const bool skip = (64 * J > ewhi) || (TY == 0 && 64 * J + 63 + 127 < ewlo);
;         if (!skip) {
;         int lim[2]; f32x4 cinit[2];
; #pragma unroll
;         for (int qb = 0; qb < 2; ++qb) {
;             lim[qb] = eq[qb] - 64 * J - 4 * fq;
;             const float c0 = TY == 0 ? -(mrun[qb] + slope2 * (float)lim[qb]) : -mrun[qb];
;             cinit[qb] = (f32x4){c0, c0, c0, c0};
;         }
;         f32x4 s[2][4];
;         bf16x8 kfr[4][NDS];
; #pragma unroll
;         for (int kb = 0; kb < 4; ++kb)
; #pragma unroll
;             for (int ds = 0; ds < NDS; ++ds) kfr[kb][ds] = *(const LAS bf16x8*)(sb + koff + (kb * NDS + ds) * 1024);
; #pragma unroll
;         for (int kb = 0; kb < 4; ++kb) {
; #pragma unroll
;             for (int ds = 0; ds < NDS; ++ds) {
;                 s[0][kb] = __builtin_amdgcn_mfma_f32_16x16x32_bf16(kfr[kb][ds], qf[0][ds], ds == 0 ? cinit[0] : s[0][kb], 0, 0, 0);
;                 s[1][kb] = __builtin_amdgcn_mfma_f32_16x16x32_bf16(kfr[kb][ds], qf[1][ds], ds == 0 ? cinit[1] : s[1][kb], 0, 0, 0);
;             }
;         }
;         bf16x8 vf[4][2];
; #pragma unroll
;         for (int db = 0; db < 4; ++db)
; #pragma unroll
;             for (int G = 0; G < 2; ++G) {
;                 LAS unsigned char* vp = sb + voff + (32 * G * VSTR + 16 * db) * 2;
;                 const v4i16_t lo = __builtin_amdgcn_ds_read_tr16_b64_v4i16((LAS v4i16_t*)vp), hi = __builtin_amdgcn_ds_read_tr16_b64_v4i16((LAS v4i16_t*)(vp + 16 * VSTR * 2));
;                 vf[db][G] = (bf16x8){lo[0], lo[1], lo[2], lo[3], hi[0], hi[1], hi[2], hi[3]};
;             }
;         if (TY == 1) {
; #pragma unroll
;             for (int kb = 0; kb < 4; ++kb) {
;                 const f32x4 fk = *(const LAS f32x4*)(sb + KBYTES + VBYTES + (16 * kb + 4 * fq) * 4);
;                 s[0][kb] -= fk; s[1][kb] -= fk;
;             }
;         }
.LBB0_763:
	s_add_i32 s24, s22, -3
	s_cmp_le_u32 s24, s20
	s_cselect_b64 s[8:9], -1, 0
	s_and_b64 vcc, exec, s[8:9]
	s_cbranch_vccz .LBB0_777
	s_add_i32 s10, s22, -1
	s_min_i32 s10, s10, s20
	s_lshl_b32 s25, s10, 6
	v_add_u32_e32 v1, s25, v169
	v_max_i32_e32 v11, 48, v1
	v_add_u32_e32 v10, s19, v1
	v_add_u32_e32 v11, s18, v11
	v_cmp_lt_i32_e32 vcc, 63, v1
	s_nop 1
	v_cndmask_b32_e32 v1, v11, v10, vcc
	v_mad_i64_i32 v[10:11], s[10:11], v1, s40, v[162:163]
	v_mad_i64_i32 v[12:13], s[10:11], v1, s40, v[164:165]
	global_load_dwordx4 v[70:73], v[10:11], off
	global_load_dwordx4 v[74:77], v[12:13], off
	v_add_u32_e32 v10, s25, v144
	v_ashrrev_i32_e32 v11, 31, v10
	v_lshlrev_b64 v[10:11], 5, v[10:11]
	v_lshl_add_u64 v[10:11], s[6:7], 0, v[10:11]
	global_load_dword v189, v[10:11], off
	s_add_i32 s10, s23, 0xffffff81
	s_cmp_gt_i32 s10, s21
	s_cbranch_scc1 .LBB0_772
	v_xor_b32_e32 v10, 0x80000000, v167
	v_xor_b32_e32 v14, 0x80000000, v166
	v_mov_b32_e32 v11, v10
	v_mov_b32_e32 v12, v10
	v_mov_b32_e32 v13, v10
	v_mov_b32_e32 v15, v14
	v_mov_b32_e32 v16, v14
	v_mov_b32_e32 v17, v14
	ds_read_b128 v[90:93], v186
	ds_read_b128 v[94:97], v186 offset:1024
	ds_read_b128 v[98:101], v186 offset:2048
	ds_read_b128 v[102:105], v186 offset:3072
	ds_read_b128 v[106:109], v186 offset:4096
	ds_read_b128 v[110:113], v186 offset:5120
	ds_read_b128 v[114:117], v186 offset:6144
	ds_read_b128 v[118:121], v186 offset:7168
	s_waitcnt lgkmcnt(7)
	v_mfma_f32_16x16x32_bf16 v[122:125], v[90:93], v[38:41], v[10:13]
	s_sub_i32 s10, s23, 64
	s_cmp_gt_i32 s10, s17
	s_mov_b64 s[10:11], -1
	v_mfma_f32_16x16x32_bf16 v[90:93], v[90:93], v[46:49], v[14:17]
	s_waitcnt lgkmcnt(6)
	v_mfma_f32_16x16x32_bf16 v[126:129], v[94:97], v[42:45], v[122:125]
	v_mfma_f32_16x16x32_bf16 v[130:133], v[94:97], v[50:53], v[90:93]
	s_waitcnt lgkmcnt(5)
	v_mfma_f32_16x16x32_bf16 v[90:93], v[98:101], v[38:41], v[10:13]
	v_mfma_f32_16x16x32_bf16 v[94:97], v[98:101], v[46:49], v[14:17]
	s_waitcnt lgkmcnt(4)
	v_mfma_f32_16x16x32_bf16 v[146:149], v[102:105], v[42:45], v[90:93]
	v_mfma_f32_16x16x32_bf16 v[190:193], v[102:105], v[50:53], v[94:97]
	s_waitcnt lgkmcnt(3)
	v_mfma_f32_16x16x32_bf16 v[90:93], v[106:109], v[38:41], v[10:13]
	v_mfma_f32_16x16x32_bf16 v[94:97], v[106:109], v[46:49], v[14:17]
	s_waitcnt lgkmcnt(1)
	v_mfma_f32_16x16x32_bf16 v[10:13], v[114:117], v[38:41], v[10:13]
	v_mfma_f32_16x16x32_bf16 v[14:17], v[114:117], v[46:49], v[14:17]
	v_mfma_f32_16x16x32_bf16 v[194:197], v[110:113], v[42:45], v[90:93]
	v_mfma_f32_16x16x32_bf16 v[122:125], v[110:113], v[50:53], v[94:97]
	s_waitcnt lgkmcnt(0)
	v_mfma_f32_16x16x32_bf16 v[140:143], v[118:121], v[42:45], v[10:13]
	v_mfma_f32_16x16x32_bf16 v[136:139], v[118:121], v[50:53], v[14:17]
	ds_read_b128 v[216:219], v188 offset:18432
	ds_read_b128 v[220:223], v188 offset:18496
	ds_read_b128 v[224:227], v188 offset:18560
	ds_read_b128 v[228:231], v188 offset:18624
	ds_read_b64_tr_b16 v[94:95], v187 offset:8192
	s_nop 0
	ds_read_b64_tr_b16 v[10:11], v187 offset:8224
	ds_read_b64_tr_b16 v[96:97], v187 offset:10752
	ds_read_b64_tr_b16 v[90:91], v187 offset:13312
	ds_read_b64_tr_b16 v[92:93], v187 offset:15872
	ds_read_b64_tr_b16 v[12:13], v187 offset:10784
	ds_read_b64_tr_b16 v[14:15], v187 offset:13344
	ds_read_b64_tr_b16 v[16:17], v187 offset:15904
	ds_read_b64_tr_b16 v[102:103], v187 offset:8256
	ds_read_b64_tr_b16 v[104:105], v187 offset:10816
	ds_read_b64_tr_b16 v[98:99], v187 offset:13376
	ds_read_b64_tr_b16 v[100:101], v187 offset:15936
	ds_read_b64_tr_b16 v[106:107], v187 offset:8288
	ds_read_b64_tr_b16 v[108:109], v187 offset:10848
	ds_read_b64_tr_b16 v[110:111], v187 offset:13408
	ds_read_b64_tr_b16 v[112:113], v187 offset:15968
	s_waitcnt lgkmcnt(15)
	s_cselect_b32 s99, 1, 0
	s_bitcmp1_b32 s41, 8
	s_cbranch_scc1 .Lfx_h0p1_end
	s_cmp_ge_u32 s24, s20
	s_cbranch_scc1 .Lfx_h0p1_bar
	s_waitcnt vmcnt(5)
	ds_write_b128 v182, v[62:65] offset:18688
	s_waitcnt vmcnt(4)
	ds_write_b128 v183, v[66:69] offset:26880
	s_and_saveexec_b64 s[100:101], s[4:5]
	s_cbranch_execz .Lfx_h0p1_w
	s_waitcnt vmcnt(3)
	ds_write_b32 v184, v185 offset:37120

; __device__ __forceinline__ unsigned cvt_pk_bf16(float lo, float hi) { f32x2 v = {lo, hi}; bf16x2_t b = __builtin_convertvector(v, bf16x2_t); return __builtin_bit_cast(unsigned, b); }
; template <int TY> __device__ __forceinline__ void attn_unit(LAS unsigned char* lds, const AttnArgs& a, int b, int h, int qt, int wave_s) {
;     ...
; #pragma unroll
;         for (int qb = 0; qb < 2; ++qb) {
; #pragma unroll
;             for (int kb = 0; kb < 4; ++kb)
; #pragma unroll
;                 for (int r = 0; r < 4; ++r) s[qb][kb][r] = __builtin_amdgcn_exp2f(s[qb][kb][r]);
; #pragma unroll
;             for (int G = 0; G < 2; ++G) {
;                 u32x4 w; w.x = cvt_pk_bf16(s[qb][2 * G][0], s[qb][2 * G][1]); w.y = cvt_pk_bf16(s[qb][2 * G][2], s[qb][2 * G][3]);
;                 w.z = cvt_pk_bf16(s[qb][2 * G + 1][0], s[qb][2 * G + 1][1]); w.w = cvt_pk_bf16(s[qb][2 * G + 1][2], s[qb][2 * G + 1][3]);
;                 pf[qb][G] = __builtin_bit_cast(bf16x8, w);
;             }
;         }
; #pragma unroll
;         for (int G = 0; G < 2; ++G) {
;             lacc[0] = __builtin_amdgcn_mfma_f32_16x16x32_bf16(ones, pf[0][G], lacc[0], 0, 0, 0);
;             lacc[1] = __builtin_amdgcn_mfma_f32_16x16x32_bf16(ones, pf[1][G], lacc[1], 0, 0, 0);
;         }
; #pragma unroll
;         for (int db = 0; db < 4; ++db)
; #pragma unroll
;             for (int G = 0; G < 2; ++G) {
;                 o[0][db] = __builtin_amdgcn_mfma_f32_16x16x32_bf16(vf[db][G], pf[0][G], o[0][db], 0, 0, 0);
;                 o[1][db] = __builtin_amdgcn_mfma_f32_16x16x32_bf16(vf[db][G], pf[1][G], o[1][db], 0, 0, 0);
;             }
.LBB0_771:
	v_exp_f32_e32 v114, v114
	v_exp_f32_e32 v115, v115
	v_exp_f32_e32 v116, v116
	v_exp_f32_e32 v117, v117
	v_exp_f32_e32 v126, v126
	v_exp_f32_e32 v127, v127
	v_exp_f32_e32 v128, v128
	v_exp_f32_e32 v129, v129
	v_cvt_pk_bf16_f32 v114, v114, v115
	v_exp_f32_e32 v18, v18
	v_exp_f32_e32 v1, v1
	v_exp_f32_e32 v20, v20
	v_exp_f32_e32 v21, v21
	v_exp_f32_e32 v115, v118
	v_exp_f32_e32 v142, v119
	v_exp_f32_e32 v143, v120
	v_exp_f32_e32 v121, v121
	v_cvt_pk_bf16_f32 v118, v18, v1
	v_cvt_pk_bf16_f32 v119, v20, v21
	v_cvt_pk_bf16_f32 v120, v115, v142
	v_cvt_pk_bf16_f32 v121, v143, v121
	v_cvt_pk_bf16_f32 v115, v116, v117
	v_cvt_pk_bf16_f32 v116, v126, v127
	v_cvt_pk_bf16_f32 v117, v128, v129
	s_waitcnt lgkmcnt(0)
	v_mfma_f32_16x16x32_bf16 v[30:33], v[10:13], v[118:121], v[30:33]
	v_exp_f32_e32 v122, v122
	v_mfma_f32_16x16x32_bf16 v[82:85], v[10:13], v[114:117], v[82:85]
	v_exp_f32_e32 v123, v123
	v_mfma_f32_16x16x32_bf16 v[26:29], v[102:105], v[118:121], v[26:29]
	v_exp_f32_e32 v124, v124
	v_mfma_f32_16x16x32_bf16 v[78:81], v[102:105], v[114:117], v[78:81]
	v_exp_f32_e32 v125, v125
	v_mfma_f32_16x16x32_bf16 v[6:9], v[54:57], v[118:121], v[6:9]
	v_exp_f32_e32 v136, v136
	v_mfma_f32_16x16x32_bf16 v[34:37], v[94:97], v[118:121], v[34:37]
	v_exp_f32_e32 v137, v137
	v_mfma_f32_16x16x32_bf16 v[86:89], v[94:97], v[114:117], v[86:89]
	v_exp_f32_e32 v138, v138
	v_mfma_f32_16x16x32_bf16 v[22:25], v[106:109], v[118:121], v[22:25]
	v_exp_f32_e32 v139, v139
	v_mfma_f32_16x16x32_bf16 v[58:61], v[106:109], v[114:117], v[58:61]
	v_cvt_pk_bf16_f32 v122, v122, v123
	v_cvt_pk_bf16_f32 v123, v124, v125
	v_mfma_f32_16x16x32_bf16 v[2:5], v[54:57], v[114:117], v[2:5]
	v_cvt_pk_bf16_f32 v124, v136, v137
	v_cvt_pk_bf16_f32 v125, v138, v139
	v_exp_f32_e32 v130, v130
	v_exp_f32_e32 v131, v131
	v_mfma_f32_16x16x32_bf16 v[30:33], v[14:17], v[122:125], v[30:33]
	v_exp_f32_e32 v132, v132
	v_mfma_f32_16x16x32_bf16 v[26:29], v[98:101], v[122:125], v[26:29]
	v_exp_f32_e32 v133, v133
	v_mfma_f32_16x16x32_bf16 v[6:9], v[54:57], v[122:125], v[6:9]
	v_exp_f32_e32 v140, v140
	v_mfma_f32_16x16x32_bf16 v[34:37], v[90:93], v[122:125], v[34:37]
	v_exp_f32_e32 v141, v141
	v_mfma_f32_16x16x32_bf16 v[22:25], v[110:113], v[122:125], v[22:25]
	v_exp_f32_e32 v1, v134
	v_exp_f32_e32 v18, v135
	v_cvt_pk_bf16_f32 v126, v130, v131
	v_cvt_pk_bf16_f32 v127, v132, v133
	v_cvt_pk_bf16_f32 v128, v140, v141
	v_cvt_pk_bf16_f32 v129, v1, v18
	s_nop 1
	v_mfma_f32_16x16x32_bf16 v[82:85], v[14:17], v[126:129], v[82:85]
	v_mfma_f32_16x16x32_bf16 v[78:81], v[98:101], v[126:129], v[78:81]
	v_mfma_f32_16x16x32_bf16 v[86:89], v[90:93], v[126:129], v[86:89]
	v_mfma_f32_16x16x32_bf16 v[58:61], v[110:113], v[126:129], v[58:61]
	v_mfma_f32_16x16x32_bf16 v[2:5], v[54:57], v[126:129], v[2:5]
	s_bitcmp1_b32 s41, 8
	s_cbranch_scc0 .LBB0_777

; #define LAS __attribute__((address_space(3)))
; template <int TY> __device__ __forceinline__ void attn_unit(LAS unsigned char* lds, const AttnArgs& a, int b, int h, int qt, int wave_s) {
;     ...
;         { const int Jn = J + 2 <= J1 ? J + 2 : J1; if (hf == 0) ATT_LOAD(A, Jn); else ATT_LOAD(B, Jn); }
;         const bool skip = (64 * J > ewhi) || (TY == 0 && 64 * J + 63 + 127 < ewlo);
;         if (!skip) {
;         int lim[2]; f32x4 cinit[2];
; #pragma unroll
;         for (int qb = 0; qb < 2; ++qb) {
;             lim[qb] = eq[qb] - 64 * J - 4 * fq;
;             const float c0 = TY == 0 ? -(mrun[qb] + slope2 * (float)lim[qb]) : -mrun[qb];
;             cinit[qb] = (f32x4){c0, c0, c0, c0};
;         }
;         f32x4 s[2][4];
;         bf16x8 kfr[4][NDS];
; #pragma unroll
;         for (int kb = 0; kb < 4; ++kb)
; #pragma unroll
;             for (int ds = 0; ds < NDS; ++ds) kfr[kb][ds] = *(const LAS bf16x8*)(sb + koff + (kb * NDS + ds) * 1024);
; #pragma unroll
;         for (int kb = 0; kb < 4; ++kb) {
; #pragma unroll
;             for (int ds = 0; ds < NDS; ++ds) {
;                 s[0][kb] = __builtin_amdgcn_mfma_f32_16x16x32_bf16(kfr[kb][ds], qf[0][ds], ds == 0 ? cinit[0] : s[0][kb], 0, 0, 0);
;                 s[1][kb] = __builtin_amdgcn_mfma_f32_16x16x32_bf16(kfr[kb][ds], qf[1][ds], ds == 0 ? cinit[1] : s[1][kb], 0, 0, 0);
;             }
;         }
;         bf16x8 vf[4][2];
; #pragma unroll
;         for (int db = 0; db < 4; ++db)
; #pragma unroll
;             for (int G = 0; G < 2; ++G) {
;                 LAS unsigned char* vp = sb + voff + (32 * G * VSTR + 16 * db) * 2;
;                 const v4i16_t lo = __builtin_amdgcn_ds_read_tr16_b64_v4i16((LAS v4i16_t*)vp), hi = __builtin_amdgcn_ds_read_tr16_b64_v4i16((LAS v4i16_t*)(vp + 16 * VSTR * 2));
;                 vf[db][G] = (bf16x8){lo[0], lo[1], lo[2], lo[3], hi[0], hi[1], hi[2], hi[3]};
;             }
;         if (TY == 1) {
; #pragma unroll
;             for (int kb = 0; kb < 4; ++kb) {
;                 const f32x4 fk = *(const LAS f32x4*)(sb + KBYTES + VBYTES + (16 * kb + 4 * fq) * 4);
;                 s[0][kb] -= fk; s[1][kb] -= fk;
;             }
;         }
.LBB0_777:
	s_andn2_b64 vcc, exec, s[8:9]
	s_cbranch_vccnz .LBB0_762
	s_cmp_ge_u32 s24, s20
	s_cbranch_scc1 .LBB0_762
	s_min_i32 s8, s22, s20
	s_lshl_b32 s10, s8, 6
	v_add_u32_e32 v1, s10, v169
	v_max_i32_e32 v11, 48, v1
	v_add_u32_e32 v10, s19, v1
	v_add_u32_e32 v11, s18, v11
	v_cmp_lt_i32_e32 vcc, 63, v1
	s_nop 1
	v_cndmask_b32_e32 v1, v11, v10, vcc
	v_mad_i64_i32 v[10:11], s[8:9], v1, s40, v[162:163]
	v_mad_i64_i32 v[12:13], s[8:9], v1, s40, v[164:165]
	global_load_dwordx4 v[62:65], v[10:11], off
	global_load_dwordx4 v[66:69], v[12:13], off
	v_add_u32_e32 v10, s10, v144
	v_ashrrev_i32_e32 v11, 31, v10
	v_lshlrev_b64 v[10:11], 5, v[10:11]
	v_lshl_add_u64 v[10:11], s[6:7], 0, v[10:11]
	global_load_dword v185, v[10:11], off
	s_sub_i32 s8, s23, 63
	s_cmp_gt_i32 s8, s21
	s_cbranch_scc1 .LBB0_787
	v_xor_b32_e32 v10, 0x80000000, v167
	v_xor_b32_e32 v14, 0x80000000, v166
	v_mov_b32_e32 v11, v10
	v_mov_b32_e32 v12, v10
	v_mov_b32_e32 v13, v10
	v_mov_b32_e32 v15, v14
	v_mov_b32_e32 v16, v14
	v_mov_b32_e32 v17, v14
	ds_read_b128 v[90:93], v186 offset:18688
	ds_read_b128 v[94:97], v186 offset:19712
	ds_read_b128 v[98:101], v186 offset:20736
	ds_read_b128 v[102:105], v186 offset:21760
	ds_read_b128 v[106:109], v186 offset:22784
	ds_read_b128 v[110:113], v186 offset:23808
	ds_read_b128 v[114:117], v186 offset:24832
	ds_read_b128 v[118:121], v186 offset:25856
	s_waitcnt lgkmcnt(7)
	v_mfma_f32_16x16x32_bf16 v[122:125], v[90:93], v[38:41], v[10:13]
	s_cmp_gt_i32 s23, s17
	s_mov_b64 s[8:9], -1
	v_mfma_f32_16x16x32_bf16 v[90:93], v[90:93], v[46:49], v[14:17]
	s_waitcnt lgkmcnt(6)
	v_mfma_f32_16x16x32_bf16 v[126:129], v[94:97], v[42:45], v[122:125]
	v_mfma_f32_16x16x32_bf16 v[130:133], v[94:97], v[50:53], v[90:93]
	s_waitcnt lgkmcnt(5)
	v_mfma_f32_16x16x32_bf16 v[90:93], v[98:101], v[38:41], v[10:13]
	v_mfma_f32_16x16x32_bf16 v[94:97], v[98:101], v[46:49], v[14:17]
	s_waitcnt lgkmcnt(4)
	v_mfma_f32_16x16x32_bf16 v[146:149], v[102:105], v[42:45], v[90:93]
	v_mfma_f32_16x16x32_bf16 v[190:193], v[102:105], v[50:53], v[94:97]
	s_waitcnt lgkmcnt(3)
	v_mfma_f32_16x16x32_bf16 v[90:93], v[106:109], v[38:41], v[10:13]
	v_mfma_f32_16x16x32_bf16 v[94:97], v[106:109], v[46:49], v[14:17]
	s_waitcnt lgkmcnt(1)
	v_mfma_f32_16x16x32_bf16 v[10:13], v[114:117], v[38:41], v[10:13]
	v_mfma_f32_16x16x32_bf16 v[14:17], v[114:117], v[46:49], v[14:17]
	v_mfma_f32_16x16x32_bf16 v[194:197], v[110:113], v[42:45], v[90:93]
	v_mfma_f32_16x16x32_bf16 v[122:125], v[110:113], v[50:53], v[94:97]
	s_waitcnt lgkmcnt(0)
	v_mfma_f32_16x16x32_bf16 v[140:143], v[118:121], v[42:45], v[10:13]
	v_mfma_f32_16x16x32_bf16 v[136:139], v[118:121], v[50:53], v[14:17]
	ds_read_b128 v[216:219], v188 offset:37120
	ds_read_b128 v[220:223], v188 offset:37184
	ds_read_b128 v[224:227], v188 offset:37248
	ds_read_b128 v[228:231], v188 offset:37312
	ds_read_b64_tr_b16 v[94:95], v187 offset:26880
	s_nop 0
	ds_read_b64_tr_b16 v[10:11], v187 offset:26912
	ds_read_b64_tr_b16 v[96:97], v187 offset:29440
	ds_read_b64_tr_b16 v[90:91], v187 offset:32000
	ds_read_b64_tr_b16 v[92:93], v187 offset:34560
	ds_read_b64_tr_b16 v[12:13], v187 offset:29472
	ds_read_b64_tr_b16 v[14:15], v187 offset:32032
	ds_read_b64_tr_b16 v[16:17], v187 offset:34592
	ds_read_b64_tr_b16 v[102:103], v187 offset:26944
	ds_read_b64_tr_b16 v[104:105], v187 offset:29504
	ds_read_b64_tr_b16 v[98:99], v187 offset:32064
	ds_read_b64_tr_b16 v[100:101], v187 offset:34624
	ds_read_b64_tr_b16 v[106:107], v187 offset:26976
	ds_read_b64_tr_b16 v[108:109], v187 offset:29536
	ds_read_b64_tr_b16 v[110:111], v187 offset:32096
	ds_read_b64_tr_b16 v[112:113], v187 offset:34656
	s_waitcnt lgkmcnt(15)
	s_cselect_b32 s99, 1, 0
	s_bitcmp1_b32 s41, 8
	s_cbranch_scc1 .Lfx_h1p1_end
	s_add_i32 s100, s22, -2
	s_cmp_ge_u32 s100, s20
	s_cbranch_scc1 .Lfx_h1p1_bar
	s_waitcnt vmcnt(5)
	ds_write_b128 v182, v[70:73]
	s_waitcnt vmcnt(4)
	ds_write_b128 v183, v[74:77] offset:8192
	s_and_saveexec_b64 s[100:101], s[4:5]
	s_cbranch_execz .Lfx_h1p1_w
	s_waitcnt vmcnt(3)
	ds_write_b32 v184, v189 offset:18432
